# GEMM epilogue stores marked sc1 (write-through) so less dirty L2 data is flushed at the phase barrier
# baseline (speedup 1.0000x reference)
.LBB0_243:
	s_or_b64 exec, exec, s[72:73]
	s_waitcnt lgkmcnt(1)
	v_cvt_pk_bf16_f32 v8, v0, v1
	v_cvt_pk_bf16_f32 v9, v2, v3
	s_waitcnt lgkmcnt(0)
	v_cvt_pk_bf16_f32 v10, v4, v5
	v_cvt_pk_bf16_f32 v11, v6, v7
	v_ashrrev_i32_e32 v25, 31, v24
	s_mov_b64 s[72:73], -1
	s_and_b64 vcc, exec, s[66:67]
	s_cbranch_vccz .LBB0_253
	v_lshlrev_b64 v[26:27], 9, v[24:25]
	v_lshl_add_u64 v[26:27], v[16:17], 0, v[26:27]
	s_and_b64 vcc, exec, s[62:63]
	s_cbranch_vccz .LBB0_248
	v_lshlrev_b32_e32 v128, 1, v12
	v_lshl_add_u64 v[32:33], v[26:27], 0, v[128:129]
	v_add_co_u32_e32 v32, vcc, 0x2c5ff000, v32
	s_nop 1
	v_addc_co_u32_e32 v33, vcc, 0, v33, vcc
	global_store_dwordx4 v[32:33], v[8:11], off offset:1536 sc1
	s_and_saveexec_b64 s[72:73], s[44:45]
	s_cbranch_execz .LBB0_247
	v_ashrrev_i32_e32 v32, 8, v24
	v_ashrrev_i32_e32 v33, 31, v32
	v_lshlrev_b64 v[32:33], 9, v[32:33]
	v_and_or_b32 v31, v24, s8, v32
	v_or_b32_e32 v33, s61, v33
	v_or_b32_e32 v32, s60, v31
	v_lshlrev_b64 v[32:33], 10, v[32:33]
	v_lshl_add_u64 v[32:33], v[18:19], 0, v[32:33]
	v_lshlrev_b32_e32 v128, 2, v12
	v_lshl_add_u64 v[32:33], v[32:33], 0, v[128:129]
	v_lshl_add_u64 v[34:35], v[32:33], 0, s[68:69]
	v_add_co_u32_e32 v32, vcc, 0xb3fe000, v32
	s_nop 1
	v_addc_co_u32_e32 v33, vcc, 0, v33, vcc
	global_store_dwordx4 v[32:33], v[0:3], off offset:3072 sc1
	global_store_dwordx4 v[34:35], v[4:7], off offset:16 sc1

.LBB0_248:
	s_andn2_b64 vcc, exec, s[72:73]
	s_cbranch_vccnz .LBB0_252
	v_lshlrev_b32_e32 v128, 1, v12
	v_lshl_add_u64 v[26:27], v[26:27], 0, v[128:129]
	v_add_co_u32_e32 v26, vcc, 0x275ff000, v26
	s_nop 1
	v_addc_co_u32_e32 v27, vcc, 0, v27, vcc
	global_store_dwordx4 v[26:27], v[8:11], off offset:2048 sc1
	s_and_saveexec_b64 s[72:73], s[44:45]
	s_cbranch_execz .LBB0_251
	v_ashrrev_i32_e32 v26, 8, v24
	v_ashrrev_i32_e32 v27, 31, v26
	v_lshlrev_b64 v[26:27], 9, v[26:27]
	v_and_or_b32 v26, v24, s8, v26
	v_or_b32_e32 v27, s61, v27
	v_or_b32_e32 v26, s60, v26
	v_lshlrev_b64 v[26:27], 10, v[26:27]
	v_lshl_add_u64 v[26:27], v[18:19], 0, v[26:27]
	v_lshlrev_b32_e32 v128, 2, v12
	v_lshl_add_u64 v[26:27], v[26:27], 0, v[128:129]
	v_lshl_add_u64 v[32:33], v[26:27], 0, s[36:37]
	v_add_co_u32_e32 v26, vcc, 0xa3ff000, v26
	s_nop 1
	v_addc_co_u32_e32 v27, vcc, 0, v27, vcc
	global_store_dwordx4 v[26:27], v[0:3], off sc1
	global_store_dwordx4 v[32:33], v[4:7], off offset:16 sc1

.LBB0_253:
	s_andn2_b64 vcc, exec, s[72:73]
	s_cbranch_vccnz .LBB0_255
	v_lshlrev_b64 v[0:1], 11, v[24:25]
	v_lshl_add_u64 v[0:1], v[20:21], 0, v[0:1]
	global_store_dwordx4 v[0:1], v[8:11], off sc1

.LBB0_259:
	s_or_b64 exec, exec, s[72:73]
	s_waitcnt lgkmcnt(1)
	v_cvt_pk_bf16_f32 v8, v0, v1
	v_cvt_pk_bf16_f32 v9, v2, v3
	s_waitcnt lgkmcnt(0)
	v_cvt_pk_bf16_f32 v10, v4, v5
	v_cvt_pk_bf16_f32 v11, v6, v7
	v_ashrrev_i32_e32 v25, 31, v24
	s_andn2_b64 vcc, exec, s[66:67]
	s_mov_b64 s[72:73], -1
	s_cbranch_vccnz .LBB0_269
	v_lshlrev_b64 v[26:27], 9, v[24:25]
	v_lshl_add_u64 v[26:27], v[16:17], 0, v[26:27]
	s_andn2_b64 vcc, exec, s[62:63]
	v_lshlrev_b32_e32 v128, 1, v12
	s_cbranch_vccnz .LBB0_264
	v_lshl_add_u64 v[30:31], v[26:27], 0, v[128:129]
	v_add_co_u32_e32 v30, vcc, 0x2c5ff000, v30
	s_nop 1
	v_addc_co_u32_e32 v31, vcc, 0, v31, vcc
	global_store_dwordx4 v[30:31], v[8:11], off offset:1536 sc1
	s_and_saveexec_b64 s[72:73], s[44:45]
	s_cbranch_execz .LBB0_263
	v_ashrrev_i32_e32 v30, 8, v24
	v_ashrrev_i32_e32 v31, 31, v30
	v_lshlrev_b64 v[30:31], 9, v[30:31]
	v_and_or_b32 v30, v24, s91, v30
	v_or_b32_e32 v31, s61, v31
	v_or_b32_e32 v30, s60, v30
	v_lshlrev_b64 v[30:31], 10, v[30:31]
	v_lshl_add_u64 v[30:31], v[18:19], 0, v[30:31]
	v_lshlrev_b32_e32 v32, 2, v12
	v_mov_b32_e32 v33, v129
	v_lshl_add_u64 v[30:31], v[30:31], 0, v[32:33]
	v_lshl_add_u64 v[32:33], v[30:31], 0, s[68:69]
	v_add_co_u32_e32 v30, vcc, 0xb3fe000, v30
	s_nop 1
	v_addc_co_u32_e32 v31, vcc, 0, v31, vcc
	global_store_dwordx4 v[30:31], v[0:3], off offset:3072 sc1
	global_store_dwordx4 v[32:33], v[4:7], off offset:16 sc1

.LBB0_264:
	s_andn2_b64 vcc, exec, s[72:73]
	s_cbranch_vccnz .LBB0_268
	v_lshl_add_u64 v[26:27], v[26:27], 0, v[128:129]
	v_add_co_u32_e32 v26, vcc, 0x275ff000, v26
	s_nop 1
	v_addc_co_u32_e32 v27, vcc, 0, v27, vcc
	global_store_dwordx4 v[26:27], v[8:11], off offset:2048 sc1
	s_and_saveexec_b64 s[72:73], s[44:45]
	s_cbranch_execz .LBB0_267
	v_ashrrev_i32_e32 v26, 8, v24
	v_ashrrev_i32_e32 v27, 31, v26
	v_lshlrev_b64 v[26:27], 9, v[26:27]
	v_and_or_b32 v26, v24, s91, v26
	v_or_b32_e32 v27, s61, v27
	v_or_b32_e32 v26, s60, v26
	v_lshlrev_b64 v[26:27], 10, v[26:27]
	v_lshl_add_u64 v[26:27], v[18:19], 0, v[26:27]
	v_lshlrev_b32_e32 v128, 2, v12
	v_lshl_add_u64 v[26:27], v[26:27], 0, v[128:129]
	v_lshl_add_u64 v[30:31], v[26:27], 0, s[36:37]
	v_add_co_u32_e32 v26, vcc, 0xa3ff000, v26
	s_nop 1
	v_addc_co_u32_e32 v27, vcc, 0, v27, vcc
	global_store_dwordx4 v[26:27], v[0:3], off sc1
	global_store_dwordx4 v[30:31], v[4:7], off offset:16 sc1

.LBB0_270:
	v_lshlrev_b64 v[0:1], 11, v[24:25]
	v_lshl_add_u64 v[0:1], v[20:21], 0, v[0:1]
	global_store_dwordx4 v[0:1], v[8:11], off sc1
	s_branch .LBB0_240

.LBB0_457:
	v_add_u32_e32 v5, s44, v4
	ds_read_b128 v[6:9], v5
	ds_read_b128 v[10:13], v5 offset:16
	v_ashrrev_i32_e32 v3, 31, v2
	s_addk_i32 s44, 0x1100
	s_cmpk_lg_i32 s44, 0x4400
	s_waitcnt lgkmcnt(1)
	v_cvt_pk_bf16_f32 v6, v6, v7
	v_cvt_pk_bf16_f32 v7, v8, v9
	s_waitcnt lgkmcnt(0)
	v_cvt_pk_bf16_f32 v8, v10, v11
	v_lshlrev_b64 v[10:11], 11, v[2:3]
	v_cvt_pk_bf16_f32 v9, v12, v13
	v_lshl_add_u64 v[10:11], v[0:1], 0, v[10:11]
	global_store_dwordx4 v[10:11], v[6:9], off sc1
	ds_read_b128 v[6:9], v5 offset:2176
	ds_read_b128 v[10:13], v5 offset:2192
	s_waitcnt lgkmcnt(1)
	v_cvt_pk_bf16_f32 v6, v6, v7
	v_cvt_pk_bf16_f32 v7, v8, v9
	s_waitcnt lgkmcnt(0)
	v_cvt_pk_bf16_f32 v8, v10, v11
	v_add_u32_e32 v10, 8, v2
	v_ashrrev_i32_e32 v11, 31, v10
	v_lshlrev_b64 v[10:11], 11, v[10:11]
	v_cvt_pk_bf16_f32 v9, v12, v13
	v_lshl_add_u64 v[10:11], v[0:1], 0, v[10:11]
	v_add_u32_e32 v2, 16, v2
	global_store_dwordx4 v[10:11], v[6:9], off sc1
	s_cbranch_scc1 .LBB0_457
	s_add_i32 s50, s50, s83
	s_add_i32 s49, s49, s83
	s_cmpk_lt_u32 s50, 0x140
	s_barrier
	s_cbranch_scc1 .LBB0_454

.LBB0_787:
	s_and_saveexec_b64 s[46:47], s[42:43]
	s_cbranch_execz .LBB0_786
	v_add_u32_e32 v17, s54, v16
	ds_read_b128 v[8:11], v17
	ds_read_b128 v[0:3], v17 offset:16
	ds_read_b128 v[18:21], v17 offset:128
	ds_read_b128 v[4:7], v17 offset:144
	s_waitcnt lgkmcnt(1)
	v_mul_f32_e32 v15, 0xbfb8aa3b, v18
	v_exp_f32_e32 v18, v15
	v_mul_f32_e32 v15, 0xbfb8aa3b, v19
	v_exp_f32_e32 v19, v15
	s_waitcnt lgkmcnt(0)
	v_mul_f32_e32 v4, 0xbfb8aa3b, v4
	v_mul_f32_e32 v5, 0xbfb8aa3b, v5
	v_exp_f32_e32 v4, v4
	v_pk_add_f32 v[18:19], v[18:19], 1.0 op_sel_hi:[1,0]
	v_exp_f32_e32 v5, v5
	v_div_scale_f32 v15, s[56:57], v19, v19, 1.0
	v_rcp_f32_e32 v22, v15
	v_pk_add_f32 v[4:5], v[4:5], 1.0 op_sel_hi:[1,0]
	v_fma_f32 v23, -v15, v22, 1.0
	v_fmac_f32_e32 v22, v23, v22
	v_div_scale_f32 v23, vcc, 1.0, v19, 1.0
	v_mul_f32_e32 v24, v23, v22
	v_fma_f32 v25, -v15, v24, v23
	v_fmac_f32_e32 v24, v25, v22
	v_fma_f32 v15, -v15, v24, v23
	v_div_fmas_f32 v15, v15, v22, v24
	v_div_fixup_f32 v19, v15, v19, 1.0
	v_div_scale_f32 v15, s[56:57], v18, v18, 1.0
	v_rcp_f32_e32 v22, v15
	s_nop 0
	v_fma_f32 v23, -v15, v22, 1.0
	v_fmac_f32_e32 v22, v23, v22
	v_div_scale_f32 v23, vcc, 1.0, v18, 1.0
	v_mul_f32_e32 v24, v23, v22
	v_fma_f32 v25, -v15, v24, v23
	v_fmac_f32_e32 v24, v25, v22
	v_fma_f32 v15, -v15, v24, v23
	v_div_fmas_f32 v15, v15, v22, v24
	v_div_fixup_f32 v18, v15, v18, 1.0
	v_mul_f32_e32 v15, 0xbfb8aa3b, v20
	v_pk_mul_f32 v[8:9], v[8:9], v[18:19]
	v_exp_f32_e32 v18, v15
	v_mul_f32_e32 v15, 0xbfb8aa3b, v21
	v_exp_f32_e32 v19, v15
	s_nop 0
	v_pk_add_f32 v[18:19], v[18:19], 1.0 op_sel_hi:[1,0]
	s_nop 0
	v_div_scale_f32 v15, s[56:57], v19, v19, 1.0
	v_rcp_f32_e32 v20, v15
	s_nop 0
	v_fma_f32 v21, -v15, v20, 1.0
	v_fmac_f32_e32 v20, v21, v20
	v_div_scale_f32 v21, vcc, 1.0, v19, 1.0
	v_mul_f32_e32 v22, v21, v20
	v_fma_f32 v23, -v15, v22, v21
	v_fmac_f32_e32 v22, v23, v20
	v_fma_f32 v15, -v15, v22, v21
	v_div_fmas_f32 v15, v15, v20, v22
	v_div_fixup_f32 v19, v15, v19, 1.0
	v_div_scale_f32 v15, s[56:57], v18, v18, 1.0
	v_rcp_f32_e32 v20, v15
	s_nop 0
	v_fma_f32 v21, -v15, v20, 1.0
	v_fmac_f32_e32 v20, v21, v20
	v_div_scale_f32 v21, vcc, 1.0, v18, 1.0
	v_mul_f32_e32 v22, v21, v20
	v_fma_f32 v23, -v15, v22, v21
	v_fmac_f32_e32 v22, v23, v20
	v_fma_f32 v15, -v15, v22, v21
	v_div_fmas_f32 v15, v15, v20, v22
	v_div_fixup_f32 v18, v15, v18, 1.0
	v_div_scale_f32 v15, s[56:57], v5, v5, 1.0
	v_pk_mul_f32 v[10:11], v[10:11], v[18:19]
	v_rcp_f32_e32 v18, v15
	s_nop 0
	v_fma_f32 v19, -v15, v18, 1.0
	v_fmac_f32_e32 v18, v19, v18
	v_div_scale_f32 v19, vcc, 1.0, v5, 1.0
	v_mul_f32_e32 v20, v19, v18
	v_fma_f32 v21, -v15, v20, v19
	v_fmac_f32_e32 v20, v21, v18
	v_fma_f32 v15, -v15, v20, v19
	v_div_fmas_f32 v15, v15, v18, v20
	v_div_fixup_f32 v5, v15, v5, 1.0
	v_div_scale_f32 v15, s[56:57], v4, v4, 1.0
	v_rcp_f32_e32 v18, v15
	s_nop 0
	v_fma_f32 v19, -v15, v18, 1.0
	v_fmac_f32_e32 v18, v19, v18
	v_div_scale_f32 v19, vcc, 1.0, v4, 1.0
	v_mul_f32_e32 v20, v19, v18
	v_fma_f32 v21, -v15, v20, v19
	v_fmac_f32_e32 v20, v21, v18
	v_fma_f32 v15, -v15, v20, v19
	v_div_fmas_f32 v15, v15, v18, v20
	v_div_fixup_f32 v4, v15, v4, 1.0
	v_pk_mul_f32 v[4:5], v[0:1], v[4:5]
	v_mul_f32_e32 v0, 0xbfb8aa3b, v6
	v_mul_f32_e32 v1, 0xbfb8aa3b, v7
	v_exp_f32_e32 v0, v0
	v_exp_f32_e32 v1, v1
	s_nop 0
	v_pk_add_f32 v[0:1], v[0:1], 1.0 op_sel_hi:[1,0]
	s_nop 0
	v_div_scale_f32 v6, s[56:57], v1, v1, 1.0
	v_rcp_f32_e32 v7, v6
	s_nop 0
	v_fma_f32 v15, -v6, v7, 1.0
	v_fmac_f32_e32 v7, v15, v7
	v_div_scale_f32 v15, vcc, 1.0, v1, 1.0
	v_mul_f32_e32 v18, v15, v7
	v_fma_f32 v19, -v6, v18, v15
	v_fmac_f32_e32 v18, v19, v7
	v_fma_f32 v6, -v6, v18, v15
	v_div_fmas_f32 v6, v6, v7, v18
	v_div_fixup_f32 v1, v6, v1, 1.0
	v_div_scale_f32 v6, s[56:57], v0, v0, 1.0
	v_rcp_f32_e32 v7, v6
	s_nop 0
	v_fma_f32 v15, -v6, v7, 1.0
	v_fmac_f32_e32 v7, v15, v7
	v_div_scale_f32 v15, vcc, 1.0, v0, 1.0
	v_mul_f32_e32 v18, v15, v7
	v_fma_f32 v19, -v6, v18, v15
	v_fmac_f32_e32 v18, v19, v7
	v_fma_f32 v6, -v6, v18, v15
	v_div_fmas_f32 v6, v6, v7, v18
	v_div_fixup_f32 v0, v6, v0, 1.0
	v_ashrrev_i32_e32 v15, 31, v14
	v_pk_mul_f32 v[6:7], v[2:3], v[0:1]
	v_cvt_pk_bf16_f32 v2, v4, v5
	v_lshlrev_b64 v[4:5], 11, v[14:15]
	v_cvt_pk_bf16_f32 v0, v8, v9
	v_cvt_pk_bf16_f32 v1, v10, v11
	v_cvt_pk_bf16_f32 v3, v6, v7
	v_lshl_add_u64 v[4:5], v[12:13], 0, v[4:5]
	global_store_dwordx4 v[4:5], v[0:3], off sc1
	ds_read_b128 v[8:11], v17 offset:2176
	ds_read_b128 v[0:3], v17 offset:2192
	ds_read_b128 v[18:21], v17 offset:2304
	ds_read_b128 v[4:7], v17 offset:2320
	s_waitcnt lgkmcnt(1)
	v_mul_f32_e32 v15, 0xbfb8aa3b, v18
	v_exp_f32_e32 v18, v15
	v_mul_f32_e32 v15, 0xbfb8aa3b, v19
	v_exp_f32_e32 v19, v15
	s_waitcnt lgkmcnt(0)
	v_mul_f32_e32 v4, 0xbfb8aa3b, v4
	v_mul_f32_e32 v5, 0xbfb8aa3b, v5
	v_exp_f32_e32 v4, v4
	v_pk_add_f32 v[18:19], v[18:19], 1.0 op_sel_hi:[1,0]
	v_exp_f32_e32 v5, v5
	v_div_scale_f32 v15, s[56:57], v19, v19, 1.0
	v_rcp_f32_e32 v17, v15
	v_pk_add_f32 v[4:5], v[4:5], 1.0 op_sel_hi:[1,0]
	v_fma_f32 v22, -v15, v17, 1.0
	v_fmac_f32_e32 v17, v22, v17
	v_div_scale_f32 v22, vcc, 1.0, v19, 1.0
	v_mul_f32_e32 v23, v22, v17
	v_fma_f32 v24, -v15, v23, v22
	v_fmac_f32_e32 v23, v24, v17
	v_fma_f32 v15, -v15, v23, v22
	v_div_fmas_f32 v15, v15, v17, v23
	v_div_fixup_f32 v19, v15, v19, 1.0
	v_div_scale_f32 v15, s[56:57], v18, v18, 1.0
	v_rcp_f32_e32 v17, v15
	s_nop 0
	v_fma_f32 v22, -v15, v17, 1.0
	v_fmac_f32_e32 v17, v22, v17
	v_div_scale_f32 v22, vcc, 1.0, v18, 1.0
	v_mul_f32_e32 v23, v22, v17
	v_fma_f32 v24, -v15, v23, v22
	v_fmac_f32_e32 v23, v24, v17
	v_fma_f32 v15, -v15, v23, v22
	v_div_fmas_f32 v15, v15, v17, v23
	v_div_fixup_f32 v18, v15, v18, 1.0
	v_mul_f32_e32 v15, 0xbfb8aa3b, v20
	v_pk_mul_f32 v[8:9], v[8:9], v[18:19]
	v_exp_f32_e32 v18, v15
	v_mul_f32_e32 v15, 0xbfb8aa3b, v21
	v_exp_f32_e32 v19, v15
	s_nop 0
	v_pk_add_f32 v[18:19], v[18:19], 1.0 op_sel_hi:[1,0]
	s_nop 0
	v_div_scale_f32 v15, s[56:57], v19, v19, 1.0
	v_rcp_f32_e32 v17, v15
	s_nop 0
	v_fma_f32 v20, -v15, v17, 1.0
	v_fmac_f32_e32 v17, v20, v17
	v_div_scale_f32 v20, vcc, 1.0, v19, 1.0
	v_mul_f32_e32 v21, v20, v17
	v_fma_f32 v22, -v15, v21, v20
	v_fmac_f32_e32 v21, v22, v17
	v_fma_f32 v15, -v15, v21, v20
	v_div_fmas_f32 v15, v15, v17, v21
	v_div_fixup_f32 v19, v15, v19, 1.0
	v_div_scale_f32 v15, s[56:57], v18, v18, 1.0
	v_rcp_f32_e32 v17, v15
	s_nop 0
	v_fma_f32 v20, -v15, v17, 1.0
	v_fmac_f32_e32 v17, v20, v17
	v_div_scale_f32 v20, vcc, 1.0, v18, 1.0
	v_mul_f32_e32 v21, v20, v17
	v_fma_f32 v22, -v15, v21, v20
	v_fmac_f32_e32 v21, v22, v17
	v_fma_f32 v15, -v15, v21, v20
	v_div_fmas_f32 v15, v15, v17, v21
	v_div_fixup_f32 v18, v15, v18, 1.0
	v_div_scale_f32 v15, s[56:57], v5, v5, 1.0
	v_rcp_f32_e32 v17, v15
	v_pk_mul_f32 v[10:11], v[10:11], v[18:19]
	v_fma_f32 v18, -v15, v17, 1.0
	v_fmac_f32_e32 v17, v18, v17
	v_div_scale_f32 v18, vcc, 1.0, v5, 1.0
	v_mul_f32_e32 v19, v18, v17
	v_fma_f32 v20, -v15, v19, v18
	v_fmac_f32_e32 v19, v20, v17
	v_fma_f32 v15, -v15, v19, v18
	v_div_fmas_f32 v15, v15, v17, v19
	v_div_fixup_f32 v5, v15, v5, 1.0
	v_div_scale_f32 v15, s[56:57], v4, v4, 1.0
	v_rcp_f32_e32 v17, v15
	s_nop 0
	v_fma_f32 v18, -v15, v17, 1.0
	v_fmac_f32_e32 v17, v18, v17
	v_div_scale_f32 v18, vcc, 1.0, v4, 1.0
	v_mul_f32_e32 v19, v18, v17
	v_fma_f32 v20, -v15, v19, v18
	v_fmac_f32_e32 v19, v20, v17
	v_fma_f32 v15, -v15, v19, v18
	v_div_fmas_f32 v15, v15, v17, v19
	v_div_fixup_f32 v4, v15, v4, 1.0
	v_pk_mul_f32 v[4:5], v[0:1], v[4:5]
	v_mul_f32_e32 v0, 0xbfb8aa3b, v6
	v_mul_f32_e32 v1, 0xbfb8aa3b, v7
	v_exp_f32_e32 v0, v0
	v_exp_f32_e32 v1, v1
	s_nop 0
	v_pk_add_f32 v[0:1], v[0:1], 1.0 op_sel_hi:[1,0]
	s_nop 0
	v_div_scale_f32 v6, s[56:57], v1, v1, 1.0
	v_rcp_f32_e32 v7, v6
	s_nop 0
	v_fma_f32 v15, -v6, v7, 1.0
	v_fmac_f32_e32 v7, v15, v7
	v_div_scale_f32 v15, vcc, 1.0, v1, 1.0
	v_mul_f32_e32 v17, v15, v7
	v_fma_f32 v18, -v6, v17, v15
	v_fmac_f32_e32 v17, v18, v7
	v_fma_f32 v6, -v6, v17, v15
	v_div_fmas_f32 v6, v6, v7, v17
	v_div_fixup_f32 v1, v6, v1, 1.0
	v_div_scale_f32 v6, s[56:57], v0, v0, 1.0
	v_rcp_f32_e32 v7, v6
	s_nop 0
	v_fma_f32 v15, -v6, v7, 1.0
	v_fmac_f32_e32 v7, v15, v7
	v_div_scale_f32 v15, vcc, 1.0, v0, 1.0
	v_mul_f32_e32 v17, v15, v7
	v_fma_f32 v18, -v6, v17, v15
	v_fmac_f32_e32 v17, v18, v7
	v_fma_f32 v6, -v6, v17, v15
	v_div_fmas_f32 v6, v6, v7, v17
	v_div_fixup_f32 v0, v6, v0, 1.0
	v_pk_mul_f32 v[6:7], v[2:3], v[0:1]
	v_cvt_pk_bf16_f32 v2, v4, v5
	v_add_u32_e32 v4, 8, v14
	v_ashrrev_i32_e32 v5, 31, v4
	v_lshlrev_b64 v[4:5], 11, v[4:5]
	v_cvt_pk_bf16_f32 v0, v8, v9
	v_cvt_pk_bf16_f32 v1, v10, v11
	v_cvt_pk_bf16_f32 v3, v6, v7
	v_lshl_add_u64 v[4:5], v[12:13], 0, v[4:5]
	global_store_dwordx4 v[4:5], v[0:3], off sc1
	s_branch .LBB0_786

.LBB0_860:
	global_load_dwordx4 v[192:195], v[8:9], off
	global_load_dwordx4 v[196:199], v[8:9], off offset:16
	v_ashrrev_i32_e32 v201, 31, v12
	v_mov_b32_e32 v200, v12
	v_lshlrev_b64 v[200:201], 11, v[200:201]
	v_lshl_add_u64 v[202:203], v[10:11], 0, v[200:201]
	global_load_dwordx4 v[218:221], v[202:203], off
	v_add_u32_e32 v200, 8, v12
	v_ashrrev_i32_e32 v201, 31, v200
	v_lshlrev_b64 v[200:201], 11, v[200:201]
	v_lshl_add_u64 v[204:205], v[10:11], 0, v[200:201]
	global_load_dwordx4 v[222:225], v[204:205], off
	v_add_u32_e32 v200, 16, v12
	v_ashrrev_i32_e32 v201, 31, v200
	v_lshlrev_b64 v[200:201], 11, v[200:201]
	v_lshl_add_u64 v[206:207], v[10:11], 0, v[200:201]
	global_load_dwordx4 v[226:229], v[206:207], off
	v_add_u32_e32 v200, 24, v12
	v_ashrrev_i32_e32 v201, 31, v200
	v_lshlrev_b64 v[200:201], 11, v[200:201]
	v_lshl_add_u64 v[208:209], v[10:11], 0, v[200:201]
	global_load_dwordx4 v[230:233], v[208:209], off
	v_add_u32_e32 v200, 32, v12
	v_ashrrev_i32_e32 v201, 31, v200
	v_lshlrev_b64 v[200:201], 11, v[200:201]
	v_lshl_add_u64 v[210:211], v[10:11], 0, v[200:201]
	global_load_dwordx4 v[234:237], v[210:211], off
	v_add_u32_e32 v200, 40, v12
	v_ashrrev_i32_e32 v201, 31, v200
	v_lshlrev_b64 v[200:201], 11, v[200:201]
	v_lshl_add_u64 v[212:213], v[10:11], 0, v[200:201]
	global_load_dwordx4 v[238:241], v[212:213], off
	v_add_u32_e32 v200, 48, v12
	v_ashrrev_i32_e32 v201, 31, v200
	v_lshlrev_b64 v[200:201], 11, v[200:201]
	v_lshl_add_u64 v[214:215], v[10:11], 0, v[200:201]
	global_load_dwordx4 v[242:245], v[214:215], off
	v_add_u32_e32 v200, 56, v12
	v_ashrrev_i32_e32 v201, 31, v200
	v_lshlrev_b64 v[200:201], 11, v[200:201]
	v_lshl_add_u64 v[216:217], v[10:11], 0, v[200:201]
	global_load_dwordx4 v[246:249], v[216:217], off
	s_waitcnt vmcnt(8)
	v_pk_add_f32 v[192:193], v[192:193], 1.0 op_sel_hi:[1,0]
	v_pk_add_f32 v[194:195], v[194:195], 1.0 op_sel_hi:[1,0]
	v_pk_add_f32 v[196:197], v[196:197], 1.0 op_sel_hi:[1,0]
	v_pk_add_f32 v[198:199], v[198:199], 1.0 op_sel_hi:[1,0]
	ds_read_b128 v[0:3], v14
	ds_read_b128 v[4:7], v14 offset:16
	s_waitcnt vmcnt(7)
	v_lshlrev_b32_e32 v16, 16, v218
	v_and_b32_e32 v17, 0xffff0000, v218
	v_lshlrev_b32_e32 v18, 16, v219
	v_and_b32_e32 v19, 0xffff0000, v219
	v_lshlrev_b32_e32 v20, 16, v220
	v_and_b32_e32 v21, 0xffff0000, v220
	v_lshlrev_b32_e32 v22, 16, v221
	v_and_b32_e32 v23, 0xffff0000, v221
	s_waitcnt lgkmcnt(0)
	v_pk_mul_f32 v[0:1], v[0:1], v[192:193]
	v_pk_mul_f32 v[2:3], v[2:3], v[194:195]
	v_pk_mul_f32 v[4:5], v[4:5], v[196:197]
	v_pk_mul_f32 v[6:7], v[6:7], v[198:199]
	v_pk_fma_f32 v[0:1], v[16:17], s[0:1], v[0:1] op_sel_hi:[1,0,1]
	v_pk_fma_f32 v[2:3], v[18:19], s[0:1], v[2:3] op_sel_hi:[1,0,1]
	v_pk_fma_f32 v[4:5], v[20:21], s[0:1], v[4:5] op_sel_hi:[1,0,1]
	v_pk_fma_f32 v[6:7], v[22:23], s[0:1], v[6:7] op_sel_hi:[1,0,1]
	s_nop 0
	v_cvt_pk_bf16_f32 v24, v0, v1
	v_cvt_pk_bf16_f32 v25, v2, v3
	v_cvt_pk_bf16_f32 v26, v4, v5
	v_cvt_pk_bf16_f32 v27, v6, v7
	global_store_dwordx4 v[202:203], v[24:27], off sc1
	s_nop 1
	ds_read_b128 v[0:3], v14 offset:2176
	ds_read_b128 v[4:7], v14 offset:2192
	s_waitcnt vmcnt(7)
	v_lshlrev_b32_e32 v16, 16, v222
	v_and_b32_e32 v17, 0xffff0000, v222
	v_lshlrev_b32_e32 v18, 16, v223
	v_and_b32_e32 v19, 0xffff0000, v223
	v_lshlrev_b32_e32 v20, 16, v224
	v_and_b32_e32 v21, 0xffff0000, v224
	v_lshlrev_b32_e32 v22, 16, v225
	v_and_b32_e32 v23, 0xffff0000, v225
	s_waitcnt lgkmcnt(0)
	v_pk_mul_f32 v[0:1], v[0:1], v[192:193]
	v_pk_mul_f32 v[2:3], v[2:3], v[194:195]
	v_pk_mul_f32 v[4:5], v[4:5], v[196:197]
	v_pk_mul_f32 v[6:7], v[6:7], v[198:199]
	v_pk_fma_f32 v[0:1], v[16:17], s[0:1], v[0:1] op_sel_hi:[1,0,1]
	v_pk_fma_f32 v[2:3], v[18:19], s[0:1], v[2:3] op_sel_hi:[1,0,1]
	v_pk_fma_f32 v[4:5], v[20:21], s[0:1], v[4:5] op_sel_hi:[1,0,1]
	v_pk_fma_f32 v[6:7], v[22:23], s[0:1], v[6:7] op_sel_hi:[1,0,1]
	s_nop 0
	v_cvt_pk_bf16_f32 v24, v0, v1
	v_cvt_pk_bf16_f32 v25, v2, v3
	v_cvt_pk_bf16_f32 v26, v4, v5
	v_cvt_pk_bf16_f32 v27, v6, v7
	global_store_dwordx4 v[204:205], v[24:27], off sc1
	s_nop 1
	ds_read_b128 v[0:3], v14 offset:4352
	ds_read_b128 v[4:7], v14 offset:4368
	s_waitcnt vmcnt(7)
	v_lshlrev_b32_e32 v16, 16, v226
	v_and_b32_e32 v17, 0xffff0000, v226
	v_lshlrev_b32_e32 v18, 16, v227
	v_and_b32_e32 v19, 0xffff0000, v227
	v_lshlrev_b32_e32 v20, 16, v228
	v_and_b32_e32 v21, 0xffff0000, v228
	v_lshlrev_b32_e32 v22, 16, v229
	v_and_b32_e32 v23, 0xffff0000, v229
	s_waitcnt lgkmcnt(0)
	v_pk_mul_f32 v[0:1], v[0:1], v[192:193]
	v_pk_mul_f32 v[2:3], v[2:3], v[194:195]
	v_pk_mul_f32 v[4:5], v[4:5], v[196:197]
	v_pk_mul_f32 v[6:7], v[6:7], v[198:199]
	v_pk_fma_f32 v[0:1], v[16:17], s[0:1], v[0:1] op_sel_hi:[1,0,1]
	v_pk_fma_f32 v[2:3], v[18:19], s[0:1], v[2:3] op_sel_hi:[1,0,1]
	v_pk_fma_f32 v[4:5], v[20:21], s[0:1], v[4:5] op_sel_hi:[1,0,1]
	v_pk_fma_f32 v[6:7], v[22:23], s[0:1], v[6:7] op_sel_hi:[1,0,1]
	s_nop 0
	v_cvt_pk_bf16_f32 v24, v0, v1
	v_cvt_pk_bf16_f32 v25, v2, v3
	v_cvt_pk_bf16_f32 v26, v4, v5
	v_cvt_pk_bf16_f32 v27, v6, v7
	global_store_dwordx4 v[206:207], v[24:27], off sc1
	s_nop 1
	ds_read_b128 v[0:3], v14 offset:6528
	ds_read_b128 v[4:7], v14 offset:6544
	s_waitcnt vmcnt(7)
	v_lshlrev_b32_e32 v16, 16, v230
	v_and_b32_e32 v17, 0xffff0000, v230
	v_lshlrev_b32_e32 v18, 16, v231
	v_and_b32_e32 v19, 0xffff0000, v231
	v_lshlrev_b32_e32 v20, 16, v232
	v_and_b32_e32 v21, 0xffff0000, v232
	v_lshlrev_b32_e32 v22, 16, v233
	v_and_b32_e32 v23, 0xffff0000, v233
	s_waitcnt lgkmcnt(0)
	v_pk_mul_f32 v[0:1], v[0:1], v[192:193]
	v_pk_mul_f32 v[2:3], v[2:3], v[194:195]
	v_pk_mul_f32 v[4:5], v[4:5], v[196:197]
	v_pk_mul_f32 v[6:7], v[6:7], v[198:199]
	v_pk_fma_f32 v[0:1], v[16:17], s[0:1], v[0:1] op_sel_hi:[1,0,1]
	v_pk_fma_f32 v[2:3], v[18:19], s[0:1], v[2:3] op_sel_hi:[1,0,1]
	v_pk_fma_f32 v[4:5], v[20:21], s[0:1], v[4:5] op_sel_hi:[1,0,1]
	v_pk_fma_f32 v[6:7], v[22:23], s[0:1], v[6:7] op_sel_hi:[1,0,1]
	s_nop 0
	v_cvt_pk_bf16_f32 v24, v0, v1
	v_cvt_pk_bf16_f32 v25, v2, v3
	v_cvt_pk_bf16_f32 v26, v4, v5
	v_cvt_pk_bf16_f32 v27, v6, v7
	global_store_dwordx4 v[208:209], v[24:27], off sc1
	s_nop 1
	ds_read_b128 v[0:3], v14 offset:8704
	ds_read_b128 v[4:7], v14 offset:8720
	s_waitcnt vmcnt(7)
	v_lshlrev_b32_e32 v16, 16, v234
	v_and_b32_e32 v17, 0xffff0000, v234
	v_lshlrev_b32_e32 v18, 16, v235
	v_and_b32_e32 v19, 0xffff0000, v235
	v_lshlrev_b32_e32 v20, 16, v236
	v_and_b32_e32 v21, 0xffff0000, v236
	v_lshlrev_b32_e32 v22, 16, v237
	v_and_b32_e32 v23, 0xffff0000, v237
	s_waitcnt lgkmcnt(0)
	v_pk_mul_f32 v[0:1], v[0:1], v[192:193]
	v_pk_mul_f32 v[2:3], v[2:3], v[194:195]
	v_pk_mul_f32 v[4:5], v[4:5], v[196:197]
	v_pk_mul_f32 v[6:7], v[6:7], v[198:199]
	v_pk_fma_f32 v[0:1], v[16:17], s[0:1], v[0:1] op_sel_hi:[1,0,1]
	v_pk_fma_f32 v[2:3], v[18:19], s[0:1], v[2:3] op_sel_hi:[1,0,1]
	v_pk_fma_f32 v[4:5], v[20:21], s[0:1], v[4:5] op_sel_hi:[1,0,1]
	v_pk_fma_f32 v[6:7], v[22:23], s[0:1], v[6:7] op_sel_hi:[1,0,1]
	s_nop 0
	v_cvt_pk_bf16_f32 v24, v0, v1
	v_cvt_pk_bf16_f32 v25, v2, v3
	v_cvt_pk_bf16_f32 v26, v4, v5
	v_cvt_pk_bf16_f32 v27, v6, v7
	global_store_dwordx4 v[210:211], v[24:27], off sc1
	s_nop 1
	ds_read_b128 v[0:3], v14 offset:10880
	ds_read_b128 v[4:7], v14 offset:10896
	s_waitcnt vmcnt(7)
	v_lshlrev_b32_e32 v16, 16, v238
	v_and_b32_e32 v17, 0xffff0000, v238
	v_lshlrev_b32_e32 v18, 16, v239
	v_and_b32_e32 v19, 0xffff0000, v239
	v_lshlrev_b32_e32 v20, 16, v240
	v_and_b32_e32 v21, 0xffff0000, v240
	v_lshlrev_b32_e32 v22, 16, v241
	v_and_b32_e32 v23, 0xffff0000, v241
	s_waitcnt lgkmcnt(0)
	v_pk_mul_f32 v[0:1], v[0:1], v[192:193]
	v_pk_mul_f32 v[2:3], v[2:3], v[194:195]
	v_pk_mul_f32 v[4:5], v[4:5], v[196:197]
	v_pk_mul_f32 v[6:7], v[6:7], v[198:199]
	v_pk_fma_f32 v[0:1], v[16:17], s[0:1], v[0:1] op_sel_hi:[1,0,1]
	v_pk_fma_f32 v[2:3], v[18:19], s[0:1], v[2:3] op_sel_hi:[1,0,1]
	v_pk_fma_f32 v[4:5], v[20:21], s[0:1], v[4:5] op_sel_hi:[1,0,1]
	v_pk_fma_f32 v[6:7], v[22:23], s[0:1], v[6:7] op_sel_hi:[1,0,1]
	s_nop 0
	v_cvt_pk_bf16_f32 v24, v0, v1
	v_cvt_pk_bf16_f32 v25, v2, v3
	v_cvt_pk_bf16_f32 v26, v4, v5
	v_cvt_pk_bf16_f32 v27, v6, v7
	global_store_dwordx4 v[212:213], v[24:27], off sc1
	s_nop 1
	ds_read_b128 v[0:3], v14 offset:13056
	ds_read_b128 v[4:7], v14 offset:13072
	s_waitcnt vmcnt(7)
	v_lshlrev_b32_e32 v16, 16, v242
	v_and_b32_e32 v17, 0xffff0000, v242
	v_lshlrev_b32_e32 v18, 16, v243
	v_and_b32_e32 v19, 0xffff0000, v243
	v_lshlrev_b32_e32 v20, 16, v244
	v_and_b32_e32 v21, 0xffff0000, v244
	v_lshlrev_b32_e32 v22, 16, v245
	v_and_b32_e32 v23, 0xffff0000, v245
	s_waitcnt lgkmcnt(0)
	v_pk_mul_f32 v[0:1], v[0:1], v[192:193]
	v_pk_mul_f32 v[2:3], v[2:3], v[194:195]
	v_pk_mul_f32 v[4:5], v[4:5], v[196:197]
	v_pk_mul_f32 v[6:7], v[6:7], v[198:199]
	v_pk_fma_f32 v[0:1], v[16:17], s[0:1], v[0:1] op_sel_hi:[1,0,1]
	v_pk_fma_f32 v[2:3], v[18:19], s[0:1], v[2:3] op_sel_hi:[1,0,1]
	v_pk_fma_f32 v[4:5], v[20:21], s[0:1], v[4:5] op_sel_hi:[1,0,1]
	v_pk_fma_f32 v[6:7], v[22:23], s[0:1], v[6:7] op_sel_hi:[1,0,1]
	s_nop 0
	v_cvt_pk_bf16_f32 v24, v0, v1
	v_cvt_pk_bf16_f32 v25, v2, v3
	v_cvt_pk_bf16_f32 v26, v4, v5
	v_cvt_pk_bf16_f32 v27, v6, v7
	global_store_dwordx4 v[214:215], v[24:27], off sc1
	s_nop 1
	ds_read_b128 v[0:3], v14 offset:15232
	ds_read_b128 v[4:7], v14 offset:15248
	s_waitcnt vmcnt(7)
	v_lshlrev_b32_e32 v16, 16, v246
	v_and_b32_e32 v17, 0xffff0000, v246
	v_lshlrev_b32_e32 v18, 16, v247
	v_and_b32_e32 v19, 0xffff0000, v247
	v_lshlrev_b32_e32 v20, 16, v248
	v_and_b32_e32 v21, 0xffff0000, v248
	v_lshlrev_b32_e32 v22, 16, v249
	v_and_b32_e32 v23, 0xffff0000, v249
	s_waitcnt lgkmcnt(0)
	v_pk_mul_f32 v[0:1], v[0:1], v[192:193]
	v_pk_mul_f32 v[2:3], v[2:3], v[194:195]
	v_pk_mul_f32 v[4:5], v[4:5], v[196:197]
	v_pk_mul_f32 v[6:7], v[6:7], v[198:199]
	v_pk_fma_f32 v[0:1], v[16:17], s[0:1], v[0:1] op_sel_hi:[1,0,1]
	v_pk_fma_f32 v[2:3], v[18:19], s[0:1], v[2:3] op_sel_hi:[1,0,1]
	v_pk_fma_f32 v[4:5], v[20:21], s[0:1], v[4:5] op_sel_hi:[1,0,1]
	v_pk_fma_f32 v[6:7], v[22:23], s[0:1], v[6:7] op_sel_hi:[1,0,1]
	s_nop 0
	v_cvt_pk_bf16_f32 v24, v0, v1
	v_cvt_pk_bf16_f32 v25, v2, v3
	v_cvt_pk_bf16_f32 v26, v4, v5
	v_cvt_pk_bf16_f32 v27, v6, v7
	global_store_dwordx4 v[216:217], v[24:27], off sc1
	s_nop 1
	s_add_i32 s54, s54, s83
	s_add_i32 s53, s53, s83
	s_cmpk_lt_u32 s54, 0x140
	s_barrier
	s_cbranch_scc1 .LBB0_857
